# attention: exact-zero skip threshold 128 log2 units with the 4-items-per-workgroup table of the previous version
# speedup vs baseline: 1.0119x; 1.0119x over previous
.Ltbl:
	s_and_b32 s0, s73, 15
	s_mov_b32 s100, 0x401a0c7c
	s_cmp_eq_u32 s0, 1
	s_cselect_b32 s100, 0x400918bb, s100
	s_cmp_eq_u32 s0, 2
	s_cselect_b32 s100, 0x403d8c3d, s100
	s_cmp_eq_u32 s0, 3
	s_cselect_b32 s100, 0x402d07ff, s100
	s_cmp_eq_u32 s0, 4
	s_cselect_b32 s100, 0x401166fe, s100
	s_cmp_eq_u32 s0, 5
	s_cselect_b32 s100, 0x401d7973, s100
	s_cmp_eq_u32 s0, 6
	s_cselect_b32 s100, 0x40014ab4, s100
	s_cmp_eq_u32 s0, 7
	s_cselect_b32 s100, 0x40228775, s100
	s_cmp_eq_u32 s0, 8
	s_cselect_b32 s100, 0x40313736, s100
	s_cmp_eq_u32 s0, 9
	s_cselect_b32 s100, 0x40252e37, s100
	s_cmp_eq_u32 s0, 10
	s_cselect_b32 s100, 0x400e98eb, s100
	s_cmp_eq_u32 s0, 11
	s_cselect_b32 s100, 0x4005a92c, s100
	s_cmp_eq_u32 s0, 12
	s_cselect_b32 s100, 0x403a1e6d, s100
	s_cmp_eq_u32 s0, 13
	s_cselect_b32 s100, 0x403559ae, s100
	s_cmp_eq_u32 s0, 14
	s_cselect_b32 s100, 0x402999ef, s100
	s_cmp_eq_u32 s0, 15
	s_cselect_b32 s100, 0x4015ecba, s100
	s_mov_b32 s74, 0
